# phase 4: Toeplitz-block build done by waves 4-7 (idle during the chunk scan) for both thread halves; scanning waves 0-3 skip it
# speedup vs baseline: 1.0105x; 1.0026x over previous
; __device__ __forceinline__ u32x4 pack8f(const float* f) { u32x4 w; w.x = cvt_pk_bf16(f[0], f[1]); w.y = cvt_pk_bf16(f[2], f[3]); w.z = cvt_pk_bf16(f[4], f[5]); w.w = cvt_pk_bf16(f[6], f[7]); return w; }
; __device__ __forceinline__ void p3_scan(Frame& F, const Args& A) {
;     ...
;     for (int i = f_gtid; i < 64 * 256 * 32; i += F.NGT) {
;         const int c8 = i & 1, s = (i >> 1) & 15, n = (i >> 5) & 255, g = i >> 13, tau = n >> 4, cp = n & 15;
;         float o[8];
; #pragma unroll
;         for (int j = 0; j < 8; ++j) o[j] = 0.f;
;         if (s <= tau) { const float* kf = Kc + ((size_t)((g * 2 + 0) * 16 + (tau - s)) * 16 + cp) * 16 + c8 * 8;
; #pragma unroll
;             for (int j = 0; j < 8; ++j) o[j] += kf[j]; }
;         if (s >= tau) { const float* kb = Kc + ((size_t)((g * 2 + 1) * 16 + (s - tau)) * 16 + cp) * 16 + c8 * 8;
; #pragma unroll
;             for (int j = 0; j < 8; ++j) o[j] += kb[j]; }
;         if (s == tau) { const float dv = Dk[g * 16 + cp];
; #pragma unroll
;             for (int j = 0; j < 8; ++j) if (c8 * 8 + j == cp) o[j] += dv; }
;         *(u32x4*)(TBT + ((size_t)(g * 256 + n) * 512 + s * 16 + c8 * 8)) = pack8f(o);
;     }
.LBB0_447:
	s_waitcnt vmcnt(0)
	v_lshl_add_u32 v11, s2, 9, v64
	s_mov_b32 s100, 0
	v_mov_b32_e32 v1, 0x80000
	v_cmp_gt_u32_e32 vcc, 0x100, v64
	s_nop 1
	v_cndmask_b32_e32 v11, v11, v1, vcc
	s_mov_b32 s3, 0x80000
	s_mov_b64 s[8:9], s[0:1]
	v_cmp_gt_i32_e32 vcc, s3, v11
	s_and_saveexec_b64 s[4:5], vcc
	s_load_dwordx2 s[82:83], s[0:1], 0x100
	v_readlane_b32 s80, v251, 12
	v_readlane_b32 s81, v251, 13
	v_readlane_b32 s18, v251, 7
	v_readlane_b32 s19, v251, 8
	s_cbranch_execz .LBB0_456
	s_load_dwordx2 s[8:9], s[8:9], 0x90
	s_waitcnt lgkmcnt(0)
	s_add_u32 s10, s6, 0x400000
	s_addc_u32 s11, s7, 0
	v_lshlrev_b32_e32 v0, 3, v64
	s_add_u32 s6, s6, 0x1100000
	v_and_b32_e32 v10, 8, v0
	s_addc_u32 s7, s7, 0
	v_mov_b32_e32 v0, 0
	v_or_b32_e32 v16, 1, v10
	v_or_b32_e32 v17, 2, v10
	v_or_b32_e32 v18, 3, v10
	v_or_b32_e32 v19, 4, v10
	v_or_b32_e32 v20, 5, v10
	v_or_b32_e32 v21, 6, v10
	v_or_b32_e32 v22, 7, v10
	s_mov_b64 s[12:13], 0
	s_mov_b32 s3, 0x7ffff
	v_lshlrev_b32_e32 v12, 2, v10
	s_branch .LBB0_450

; __device__ __forceinline__ void xcd_barrier(const XcdBarrier& b) {
;     asm volatile("s_waitcnt vmcnt(0)" ::: "memory");
;     __syncthreads();
;     if (threadIdx.x == 0) {
;         unsigned* bar = b.bar;
;         __builtin_amdgcn_s_waitcnt(0);
;         unsigned nloc = b.st[0], nx = b.st[1];
;         if (nloc == 0u) { xcd_barrier_complete(bar, b.x, nloc, nx); b.st[0] = nloc; b.st[1] = nx; }
.LBB0_456:
	s_or_b64 exec, exec, s[4:5]
	s_cmp_lg_u32 s100, 0
	s_cbranch_scc1 .Ltbt_done
	s_mov_b32 s100, 1
	v_lshl_add_u32 v11, s2, 9, v64
	v_add_u32_e32 v11, 0xffffff00, v11
	v_mov_b32_e32 v1, 0x80000
	v_cmp_gt_u32_e32 vcc, 0x100, v64
	s_nop 1
	v_cndmask_b32_e32 v11, v11, v1, vcc
	v_cmp_gt_i32_e32 vcc, 0x80000, v11
	s_and_saveexec_b64 s[4:5], vcc
	s_cbranch_execz .LBB0_456
	s_mov_b64 s[12:13], 0
	s_branch .LBB0_450
.Ltbt_done:
	s_mov_b64 s[4:5], s[0:1]
	s_load_dword s3, s[4:5], 0xf8
	v_readlane_b32 s86, v251, 9
	v_readlane_b32 s76, v251, 5
	v_readlane_b32 s84, v251, 11
	v_readlane_b32 s87, v251, 10
	s_waitcnt lgkmcnt(0)
	s_cmp_gt_i32 s3, 5
	v_readlane_b32 s77, v251, 6
	s_cbranch_scc1 .LBB0_511
	s_mov_b64 s[4:5], s[0:1]
	s_load_dword s3, s[4:5], 0xfc
	s_waitcnt lgkmcnt(0)
	s_cmp_lt_i32 s3, 6
	s_cbranch_scc1 .LBB0_511
	s_waitcnt vmcnt(0)
	s_barrier
	s_and_saveexec_b64 s[4:5], s[80:81]
	s_cbranch_execz .LBB0_510
	v_readlane_b32 s6, v251, 0
	v_readlane_b32 s7, v251, 1
	s_add_u32 s6, s6, 0x80200
	s_addc_u32 s7, s7, 0
	s_add_i32 s3, 0, 0x20040
	v_mov_b32_e32 v0, s3
	s_waitcnt vmcnt(0) expcnt(0) lgkmcnt(0)
	ds_read_b32 v2, v0
	s_add_i32 s3, 0, 0x20044
	v_mov_b32_e32 v0, s3
	ds_read_b32 v0, v0
	s_waitcnt lgkmcnt(1)
	v_cmp_ne_u32_e32 vcc, 0, v2
	s_cbranch_vccnz .LBB0_474
	s_load_dword s8, s[0:1], 0x108
	s_mul_i32 s3, s83, s82
	v_readlane_b32 s40, v251, 0
	v_readlane_b32 s41, v251, 1
	s_mov_b32 s33, 1
	s_waitcnt lgkmcnt(0)
	s_mul_i32 s3, s3, s8
	s_add_u32 s8, s40, 0x80400
	s_addc_u32 s9, s41, 0
	s_add_u32 s10, s40, 0x80500
	s_addc_u32 s11, s41, 0
	s_add_u32 s12, s40, 0x80600
	s_addc_u32 s13, s41, 0
	s_add_u32 s14, s40, 0x80700
	s_addc_u32 s15, s41, 0
	s_add_u32 s16, s40, 0x80800
	s_addc_u32 s17, s41, 0
	s_add_u32 s18, s40, 0x80900
	s_addc_u32 s19, s41, 0
	s_add_u32 s20, s40, 0x80a00
	s_addc_u32 s21, s41, 0
	s_add_u32 s22, s40, 0x80b00
	s_addc_u32 s23, s41, 0
	s_add_u32 s24, s40, 0x80c00
	s_addc_u32 s25, s41, 0
	s_add_u32 s26, s40, 0x80d00
	s_addc_u32 s27, s41, 0
	s_add_u32 s28, s40, 0x80e00
	s_addc_u32 s29, s41, 0
	s_add_u32 s30, s40, 0x80f00
	s_addc_u32 s31, s41, 0
	s_add_u32 s34, s40, 0x81000
	s_addc_u32 s35, s41, 0
	s_add_u32 s36, s40, 0x81100
	s_addc_u32 s37, s41, 0
	s_add_u32 s38, s40, 0x81200
	s_addc_u32 s39, s41, 0
	s_add_u32 s40, s40, 0x81300
	s_addc_u32 s41, s41, 0
	v_mov_b32_e32 v16, 0
	s_branch .LBB0_462
